# PEER leader wave: s_setprio 3 with shorter per-unit leader sleep (s_sleep 2 instead of 3)
# baseline (speedup 1.0000x reference)
.Lxp_unit:
	s_cmp_eq_u32 s82, 1
	s_cbranch_scc0 .Lxp_fola
	s_lshl_b32 s2, s25, 7
	s_add_i32 s2, s2, s97
	s_and_b32 s2, s2, 0x3fff
	v_mov_b32_e32 v245, s2
	s_mov_b64 exec, 1
	global_store_dword v[246:247], v245, off
	s_mov_b64 exec, -1
	s_sleep 2
	s_branch .Lxp_syncda

.Lxp_noswa:
	s_mov_b32 s80, s81
	s_mov_b32 s81, s94
	s_add_i32 s25, s25, 1
	s_cmp_eq_u32 s82, 1
	s_cbranch_scc0 .Lxp_folb
	s_lshl_b32 s2, s25, 7
	s_add_i32 s2, s2, s97
	s_and_b32 s2, s2, 0x3fff
	v_mov_b32_e32 v245, s2
	s_mov_b64 exec, 1
	global_store_dword v[246:247], v245, off
	s_mov_b64 exec, -1
	s_sleep 2
	s_branch .Lxp_syncdb

.Lxp_noswc:
	s_mov_b32 s80, s81
	s_mov_b32 s81, s94
	s_add_i32 s25, s25, 1
	s_cmp_lt_u32 s25, 126
	s_cbranch_scc1 .Lxp_unit
	s_cmp_eq_u32 s82, 1
	s_cbranch_scc0 .Lxp_fold
	s_lshl_b32 s2, s25, 7
	s_add_i32 s2, s2, s97
	s_and_b32 s2, s2, 0x3fff
	v_mov_b32_e32 v245, s2
	s_mov_b64 exec, 1
	global_store_dword v[246:247], v245, off
	s_mov_b64 exec, -1
	s_sleep 2
	s_branch .Lxp_syncdd
